# PH4 tile loop: waves 4-7 run the tile body rotated by half an iteration (three LDS tile buffers, one barrier per iteration)
# speedup vs baseline: 1.0121x; 1.0115x over previous
; template <bool MASK>
; DI void attn_unit(LAS unsigned char* lds, const bf16_t* qrow, const bf16_t* kbase, int kpitch, const bf16_t* vtbase, int vtpitch, int ntiles,
;                   const unsigned long long* maskp, bf16_t* orow, float c1, float c2) {
;     ...
;     unsigned long long mw_next = ~0ull;
;     if (MASK) mw_next = maskp[0];
;     __syncthreads();
;     for (int kt = 0; kt < ntiles; ++kt) {
;         const bool more = kt + 1 < ntiles;
;         if (more) {
;             const size_t ko = (size_t)(kt + 1) * 64 * kpitch; const int vo = (kt + 1) * 64;
;             pk[0] = *(const u32x4*)(kg0 + ko); pk[1] = *(const u32x4*)(kg1 + ko); pv[0] = *(const u32x4*)(vg0 + vo); pv[1] = *(const u32x4*)(vg1 + vo);
;         }
;         const unsigned long long mw = mw_next;
;         if (MASK && more) mw_next = maskp[(size_t)(kt + 1) * S_];
.LBB0_1243:
	v_mov_b32_e32 v63, 0
	s_andn2_b64 vcc, exec, s[2:3]
	v_mov_b32_e32 v62, v63
	v_mov_b32_e32 v61, v63
	v_mov_b32_e32 v60, v63
	v_mov_b32_e32 v59, v63
	v_mov_b32_e32 v58, v63
	v_mov_b32_e32 v57, v63
	v_mov_b32_e32 v56, v63
	v_mov_b32_e32 v55, v63
	v_mov_b32_e32 v54, v63
	v_mov_b32_e32 v53, v63
	v_mov_b32_e32 v52, v63
	v_mov_b32_e32 v51, v63
	v_mov_b32_e32 v50, v63
	v_mov_b32_e32 v49, v63
	v_mov_b32_e32 v48, v63
	v_mov_b32_e32 v47, v63
	v_mov_b32_e32 v46, v63
	v_mov_b32_e32 v45, v63
	v_mov_b32_e32 v44, v63
	v_mov_b32_e32 v43, v63
	v_mov_b32_e32 v42, v63
	v_mov_b32_e32 v41, v63
	v_mov_b32_e32 v40, v63
	v_mov_b32_e32 v39, v63
	v_mov_b32_e32 v38, v63
	v_mov_b32_e32 v37, v63
	v_mov_b32_e32 v36, v63
	v_mov_b32_e32 v35, v63
	v_mov_b32_e32 v34, v63
	v_mov_b32_e32 v33, v63
	v_mov_b32_e32 v32, v63
	v_mov_b32_e32 v31, v63
	v_mov_b32_e32 v30, v63
	v_mov_b32_e32 v29, v63
	v_mov_b32_e32 v28, v63
	v_mov_b32_e32 v27, v63
	v_mov_b32_e32 v26, v63
	v_mov_b32_e32 v25, v63
	v_mov_b32_e32 v24, v63
	v_mov_b32_e32 v23, v63
	v_mov_b32_e32 v22, v63
	v_mov_b32_e32 v21, v63
	v_mov_b32_e32 v20, v63
	v_mov_b32_e32 v19, v63
	v_mov_b32_e32 v18, v63
	v_mov_b32_e32 v17, v63
	v_mov_b32_e32 v16, v63
	v_mov_b32_e32 v15, v63
	v_mov_b32_e32 v14, v63
	v_mov_b32_e32 v13, v63
	v_mov_b32_e32 v12, v63
	v_mov_b32_e32 v11, v63
	v_mov_b32_e32 v10, v63
	v_mov_b32_e32 v9, v63
	v_mov_b32_e32 v8, v63
	v_mov_b32_e32 v7, v63
	v_mov_b32_e32 v6, v63
	v_mov_b32_e32 v5, v63
	v_mov_b32_e32 v4, v63
	v_mov_b32_e32 v3, v63
	v_mov_b32_e32 v2, v63
	v_mov_b32_e32 v1, v63
	v_mov_b32_e32 v0, v63
	v_mov_b32_e32 v149, v63
	s_mov_b64 s[30:31], 0x8000
	s_cbranch_vccnz .LBB0_1238
	s_add_i32 s17, s16, 1
	s_add_u32 s2, s18, s22
	s_addc_u32 s3, 0, 0
	s_add_u32 s2, s2, 0x20908000
	v_and_b32_e32 v0, 31, v65
	s_addc_u32 s3, s3, 0
	v_and_b32_e32 v2, 15, v65
	v_mul_u32_u24_e32 v153, 0x110, v0
	v_mul_u32_u24_e32 v180, 0x88, v0
	v_lshl_add_u64 v[0:1], s[2:3], 0, v[68:69]
	v_lshlrev_b32_e32 v2, 4, v2
	v_mov_b32_e32 v3, v161
	v_lshl_add_u64 v[154:155], v[0:1], 0, v[2:3]
	v_lshl_add_u64 v[0:1], s[2:3], 0, v[70:71]
	s_add_u32 s2, s19, 0x21100080
	v_lshl_add_u64 v[156:157], v[0:1], 0, v[2:3]
	s_addc_u32 s3, 0, 0
	v_and_b32_e32 v2, 7, v65
	v_lshl_add_u64 v[0:1], s[2:3], 0, v[72:73]
	v_lshlrev_b32_e32 v2, 4, v2
	v_lshl_add_u64 v[158:159], v[0:1], 0, v[2:3]
	v_lshl_add_u64 v[0:1], s[2:3], 0, v[74:75]
	s_add_u32 s2, s18, 0x23e08000
	s_addc_u32 s3, 0, 0
	v_mov_b32_e32 v149, 0
	v_lshlrev_b32_e32 v151, 3, v76
	v_lshl_add_u64 v[170:171], v[0:1], 0, v[2:3]
	v_lshl_add_u64 v[172:173], v[66:67], 3, s[2:3]
	s_mov_b32 s18, 0
	v_mov_b32_e32 v0, 0
	v_mov_b32_e32 v1, v149
	v_mov_b32_e32 v2, v149
	v_mov_b32_e32 v3, v149
	v_mov_b32_e32 v4, v149
	v_mov_b32_e32 v5, v149
	v_mov_b32_e32 v6, v149
	v_mov_b32_e32 v7, v149
	v_mov_b32_e32 v8, v149
	v_mov_b32_e32 v9, v149
	v_mov_b32_e32 v10, v149
	v_mov_b32_e32 v11, v149
	v_mov_b32_e32 v12, v149
	v_mov_b32_e32 v13, v149
	v_mov_b32_e32 v14, v149
	v_mov_b32_e32 v15, v149
	v_mov_b32_e32 v16, 0
	v_mov_b32_e32 v17, v149
	v_mov_b32_e32 v18, v149
	v_mov_b32_e32 v19, v149
	v_mov_b32_e32 v20, v149
	v_mov_b32_e32 v21, v149
	v_mov_b32_e32 v22, v149
	v_mov_b32_e32 v23, v149
	v_mov_b32_e32 v24, v149
	v_mov_b32_e32 v25, v149
	v_mov_b32_e32 v26, v149
	v_mov_b32_e32 v27, v149
	v_mov_b32_e32 v28, v149
	v_mov_b32_e32 v29, v149
	v_mov_b32_e32 v30, v149
	v_mov_b32_e32 v31, v149
	v_mov_b32_e32 v32, 0
	v_mov_b32_e32 v33, v149
	v_mov_b32_e32 v34, v149
	v_mov_b32_e32 v35, v149
	v_mov_b32_e32 v36, v149
	v_mov_b32_e32 v37, v149
	v_mov_b32_e32 v38, v149
	v_mov_b32_e32 v39, v149
	v_mov_b32_e32 v40, v149
	v_mov_b32_e32 v41, v149
	v_mov_b32_e32 v42, v149
	v_mov_b32_e32 v43, v149
	v_mov_b32_e32 v44, v149
	v_mov_b32_e32 v45, v149
	v_mov_b32_e32 v46, v149
	v_mov_b32_e32 v47, v149
	v_mov_b32_e32 v48, 0
	v_mov_b32_e32 v49, v149
	v_mov_b32_e32 v50, v149
	v_mov_b32_e32 v51, v149
	v_mov_b32_e32 v52, v149
	v_mov_b32_e32 v53, v149
	v_mov_b32_e32 v54, v149
	v_mov_b32_e32 v55, v149
	v_mov_b32_e32 v56, v149
	v_mov_b32_e32 v57, v149
	v_mov_b32_e32 v58, v149
	v_mov_b32_e32 v59, v149
	v_mov_b32_e32 v60, v149
	v_mov_b32_e32 v61, v149
	v_mov_b32_e32 v62, v149
	v_mov_b32_e32 v63, v149
	s_waitcnt vmcnt(0)
	v_mov_b64_e32 v[174:175], v[176:177]
	v_readfirstlane_b32 s20, v186
	s_mov_b32 s21, 0
	s_mov_b32 s23, 0x8800
	s_mov_b32 s24, 0x11000
	s_bfe_u32 s20, s20, 0x10008
	s_cmp_eq_u32 s20, 0
	s_cbranch_scc1 .Lat_top
	s_mov_b32 s2, 0xffff8000
	s_mov_b32 s3, -1
	v_lshl_add_u64 v[172:173], v[172:173], 0, s[2:3]
.Lat_top:
	s_cmp_lt_i32 s18, s16
	s_cbranch_scc0 .Lat_noload
	v_lshl_add_u64 v[204:205], s[0:1], 0, v[154:155]
	v_lshl_add_u64 v[206:207], s[0:1], 0, v[156:157]
	v_lshl_add_u64 v[208:209], s[0:1], 0, v[158:159]
	v_lshl_add_u64 v[210:211], s[0:1], 0, v[170:171]
	global_load_dwordx4 v[96:99], v[204:205], off
	global_load_dwordx4 v[100:103], v[206:207], off
	global_load_dwordx4 v[104:107], v[208:209], off
	global_load_dwordx4 v[108:111], v[210:211], off
	v_lshl_add_u64 v[154:155], v[154:155], 0, s[30:31]
	v_lshl_add_u64 v[156:157], v[156:157], 0, s[30:31]
	v_lshl_add_u64 v[158:159], v[158:159], 0, s[78:79]
	v_lshl_add_u64 v[170:171], v[170:171], 0, s[78:79]
.Lat_noload:
	s_add_i32 s2, s16, s20
	s_cmp_lt_i32 s18, s2
	s_cbranch_scc0 .Lat_nomask
	v_lshl_add_u64 v[204:205], s[0:1], 0, v[172:173]
	global_load_dwordx2 v[174:175], v[204:205], off
	v_lshl_add_u64 v[172:173], v[172:173], 0, s[30:31]
; #define LAS __attribute__((address_space(3)))
; DI unsigned pk2(float lo, float hi) { f32x2 v = {lo, hi}; bf16x2_t b = __builtin_convertvector(v, bf16x2_t); return __builtin_bit_cast(unsigned, b); }
; template <bool MASK>
; DI void attn_unit(LAS unsigned char* lds, const bf16_t* qrow, const bf16_t* kbase, int kpitch, const bf16_t* vtbase, int vtpitch, int ntiles,
;                   const unsigned long long* maskp, bf16_t* orow, float c1, float c2) {
;     ...
;         f32x16 xs[2];
; #pragma unroll
;         for (int sub = 0; sub < 2; ++sub) {
; #pragma unroll
;             for (int i = 0; i < 16; ++i) xs[sub][i] = 0.f;
;             __builtin_amdgcn_s_setprio(1);
; #pragma unroll
;             for (int ks = 0; ks < 8; ++ks) {
;                 const bf16x8 a = *(const LAS bf16x8*)(buf + (32 * sub + r) * AK_PITCH + ks * 32 + h * 16);
;                 xs[sub] = __builtin_amdgcn_mfma_f32_32x32x16_bf16(a, qf[ks], xs[sub], 0, 0, 0);
;             }
;             __builtin_amdgcn_s_setprio(0);
;         }
; #pragma unroll
;         for (int sub = 0; sub < 2; ++sub) {
;             const unsigned mws = ((unsigned)(mw >> (32 * sub))) >> (4 * h);
;             float pe[16];
; #pragma unroll
;             for (int i = 0; i < 16; ++i) {
;                 float p = __builtin_amdgcn_exp2f(xs[sub][i] * c1 - c2);
;                 if (MASK) { const int m = __builtin_amdgcn_sbfe((int)mws, (i & 3) + 8 * (i >> 2), 1); p = __uint_as_float(__float_as_uint(p) & (unsigned)m); }
;                 l += p; pe[i] = p;
;             }
;             u32x4 p0, p1;
;             p0.x = pk2(pe[0], pe[1]); p0.y = pk2(pe[2], pe[3]); p0.z = pk2(pe[4], pe[5]); p0.w = pk2(pe[6], pe[7]);
;             p1.x = pk2(pe[8], pe[9]); p1.y = pk2(pe[10], pe[11]); p1.z = pk2(pe[12], pe[13]); p1.w = pk2(pe[14], pe[15]);
.Lat_nomask:
	s_cmp_eq_u32 s20, 0
	s_cbranch_scc0 .Lat_grpb
	s_cmp_lt_i32 s18, s17
	s_cbranch_scc0 .Lat_bottom
	s_setprio 1
	v_add3_u32 v166, s21, v160, v153
	ds_read_b128 v[212:215], v166
	ds_read_b128 v[216:219], v166 offset:32
	ds_read_b128 v[220:223], v166 offset:64
	ds_read_b128 v[224:227], v166 offset:96
	ds_read_b128 v[228:231], v166 offset:128
	ds_read_b128 v[232:235], v166 offset:160
	ds_read_b128 v[236:239], v166 offset:192
	ds_read_b128 v[240:243], v166 offset:224
	ds_read_b128 v[244:247], v166 offset:8704
	ds_read_b128 v[248:251], v166 offset:8736
	ds_read_b128 v[200:203], v166 offset:8768
	ds_read_b128 v[204:207], v166 offset:8800
	ds_read_b128 v[208:211], v166 offset:8832
	ds_read_b128 v[182:185], v166 offset:8864
	s_waitcnt lgkmcnt(13)
	v_mfma_f32_32x32x16_bf16 v[80:95], v[212:215], v[112:115], 0
	s_waitcnt lgkmcnt(12)
	v_mfma_f32_32x32x16_bf16 v[80:95], v[216:219], v[116:119], v[80:95]
	ds_read_b128 v[212:215], v166 offset:8896
	ds_read_b128 v[216:219], v166 offset:8928
	s_waitcnt lgkmcnt(13)
	v_mfma_f32_32x32x16_bf16 v[80:95], v[220:223], v[120:123], v[80:95]
	s_waitcnt lgkmcnt(12)
	v_mfma_f32_32x32x16_bf16 v[80:95], v[224:227], v[124:127], v[80:95]
	s_waitcnt lgkmcnt(11)
	v_mfma_f32_32x32x16_bf16 v[80:95], v[228:231], v[128:131], v[80:95]
	s_waitcnt lgkmcnt(10)
	v_mfma_f32_32x32x16_bf16 v[80:95], v[232:235], v[132:135], v[80:95]
	s_waitcnt lgkmcnt(9)
	v_mfma_f32_32x32x16_bf16 v[80:95], v[236:239], v[136:139], v[80:95]
	s_waitcnt lgkmcnt(8)
	v_mfma_f32_32x32x16_bf16 v[80:95], v[240:243], v[140:143], v[80:95]
	s_waitcnt lgkmcnt(7)
	v_mfma_f32_32x32x16_bf16 v[64:79], v[244:247], v[112:115], 0
	s_waitcnt lgkmcnt(6)
	v_mfma_f32_32x32x16_bf16 v[64:79], v[248:251], v[116:119], v[64:79]
	s_waitcnt lgkmcnt(5)
	v_mfma_f32_32x32x16_bf16 v[64:79], v[200:203], v[120:123], v[64:79]
	s_waitcnt lgkmcnt(4)
	v_mfma_f32_32x32x16_bf16 v[64:79], v[204:207], v[124:127], v[64:79]
	s_waitcnt lgkmcnt(3)
	v_mfma_f32_32x32x16_bf16 v[64:79], v[208:211], v[128:131], v[64:79]
	s_waitcnt lgkmcnt(2)
	v_mfma_f32_32x32x16_bf16 v[64:79], v[182:185], v[132:135], v[64:79]
	s_waitcnt lgkmcnt(1)
	v_mfma_f32_32x32x16_bf16 v[64:79], v[212:215], v[136:139], v[64:79]
	s_waitcnt lgkmcnt(0)
	v_mfma_f32_32x32x16_bf16 v[64:79], v[216:219], v[140:143], v[64:79]
	s_setprio 0
	v_add3_u32 v166, s21, v151, v180
	v_lshrrev_b32_e32 v204, v147, v176
	v_lshrrev_b32_e32 v205, v147, v177
	v_add_u32_e32 v167, 0x4000, v166
	v_add_u32_e32 v168, 0x5000, v166
	v_add_u32_e32 v169, 0x6000, v166
	v_add_u32_e32 v199, 0x7000, v166
	ds_read2_b64 v[220:223], v167 offset0:128 offset1:130
	ds_read2_b64 v[224:227], v167 offset0:132 offset1:134
	ds_read2_b64 v[228:231], v168 offset0:160 offset1:162
	ds_read2_b64 v[232:235], v168 offset0:164 offset1:166
	ds_read2_b64 v[236:239], v169 offset0:192 offset1:194
	ds_read2_b64 v[240:243], v169 offset0:196 offset1:198
	ds_read2_b64 v[244:247], v199 offset0:224 offset1:226
	ds_read2_b64 v[248:251], v199 offset0:228 offset1:230
	v_fma_f32 v80, v80, s95, -v178
	v_exp_f32_e32 v80, v80
	v_bfe_i32 v206, v204, 0, 1
	v_fma_f32 v81, v81, s95, -v178
	v_exp_f32_e32 v81, v81
	v_bfe_i32 v207, v204, 1, 1
	v_and_b32_e32 v80, v80, v206
	v_fma_f32 v82, v82, s95, -v178
	v_exp_f32_e32 v82, v82
	v_bfe_i32 v208, v204, 2, 1
	v_and_b32_e32 v81, v81, v207
	v_fma_f32 v83, v83, s95, -v178
	v_exp_f32_e32 v83, v83
	v_bfe_i32 v209, v204, 3, 1
	v_and_b32_e32 v82, v82, v208
	v_fma_f32 v84, v84, s95, -v178
	v_exp_f32_e32 v84, v84
	v_bfe_i32 v210, v204, 8, 1
	v_and_b32_e32 v83, v83, v209
	v_fma_f32 v85, v85, s95, -v178
	v_exp_f32_e32 v85, v85
	v_bfe_i32 v211, v204, 9, 1
	v_and_b32_e32 v84, v84, v210
	v_fma_f32 v86, v86, s95, -v178
	v_exp_f32_e32 v86, v86
	v_bfe_i32 v206, v204, 10, 1
	v_and_b32_e32 v85, v85, v211
	v_fma_f32 v87, v87, s95, -v178
	v_exp_f32_e32 v87, v87
	v_bfe_i32 v207, v204, 11, 1
	v_and_b32_e32 v86, v86, v206
	v_fma_f32 v88, v88, s95, -v178
	v_exp_f32_e32 v88, v88
	v_bfe_i32 v208, v204, 16, 1
	v_and_b32_e32 v87, v87, v207
	v_fma_f32 v89, v89, s95, -v178
	v_exp_f32_e32 v89, v89
	v_bfe_i32 v209, v204, 17, 1
	v_and_b32_e32 v88, v88, v208
	v_fma_f32 v90, v90, s95, -v178
	v_exp_f32_e32 v90, v90
	v_bfe_i32 v210, v204, 18, 1
	v_and_b32_e32 v89, v89, v209
	v_fma_f32 v91, v91, s95, -v178
	v_exp_f32_e32 v91, v91
	v_bfe_i32 v211, v204, 19, 1
	v_and_b32_e32 v90, v90, v210
	v_fma_f32 v92, v92, s95, -v178
	v_exp_f32_e32 v92, v92
	v_bfe_i32 v206, v204, 24, 1
	v_and_b32_e32 v91, v91, v211
	v_fma_f32 v93, v93, s95, -v178
	v_exp_f32_e32 v93, v93
	v_bfe_i32 v207, v204, 25, 1
	v_and_b32_e32 v92, v92, v206
	v_fma_f32 v94, v94, s95, -v178
	v_exp_f32_e32 v94, v94
	v_bfe_i32 v208, v204, 26, 1
	v_and_b32_e32 v93, v93, v207
	v_fma_f32 v95, v95, s95, -v178
	v_exp_f32_e32 v95, v95
	v_bfe_i32 v209, v204, 27, 1
	v_and_b32_e32 v94, v94, v208
	v_nop
	v_and_b32_e32 v95, v95, v209
	v_cvt_pk_bf16_f32 v182, v80, v81
	v_cvt_pk_bf16_f32 v183, v82, v83
	v_cvt_pk_bf16_f32 v184, v84, v85
	v_cvt_pk_bf16_f32 v185, v86, v87
	v_cvt_pk_bf16_f32 v200, v88, v89
	v_cvt_pk_bf16_f32 v201, v90, v91
	v_cvt_pk_bf16_f32 v202, v92, v93
	v_cvt_pk_bf16_f32 v203, v94, v95
	v_pk_add_f32 v[80:81], v[80:81], v[82:83]
	v_pk_add_f32 v[84:85], v[84:85], v[86:87]
	v_pk_add_f32 v[88:89], v[88:89], v[90:91]
	v_pk_add_f32 v[92:93], v[92:93], v[94:95]
	v_pk_add_f32 v[80:81], v[80:81], v[84:85]
	v_pk_add_f32 v[88:89], v[88:89], v[92:93]
	v_pk_add_f32 v[80:81], v[80:81], v[88:89]
	v_add_f32_e32 v80, v80, v81
	v_add_f32_e32 v149, v149, v80
	s_waitcnt lgkmcnt(0)
; #define LAS __attribute__((address_space(3)))
; DI unsigned pk2(float lo, float hi) { f32x2 v = {lo, hi}; bf16x2_t b = __builtin_convertvector(v, bf16x2_t); return __builtin_bit_cast(unsigned, b); }
; template <bool MASK>
; DI void attn_unit(LAS unsigned char* lds, const bf16_t* qrow, const bf16_t* kbase, int kpitch, const bf16_t* vtbase, int vtpitch, int ntiles,
;                   const unsigned long long* maskp, bf16_t* orow, float c1, float c2) {
;     ...
;         for (int sub = 0; sub < 2; ++sub) {
;             const unsigned mws = ((unsigned)(mw >> (32 * sub))) >> (4 * h);
;             float pe[16];
; #pragma unroll
;             for (int i = 0; i < 16; ++i) {
;                 float p = __builtin_amdgcn_exp2f(xs[sub][i] * c1 - c2);
;                 if (MASK) { const int m = __builtin_amdgcn_sbfe((int)mws, (i & 3) + 8 * (i >> 2), 1); p = __uint_as_float(__float_as_uint(p) & (unsigned)m); }
;                 l += p; pe[i] = p;
;             }
;             u32x4 p0, p1;
;             p0.x = pk2(pe[0], pe[1]); p0.y = pk2(pe[2], pe[3]); p0.z = pk2(pe[4], pe[5]); p0.w = pk2(pe[6], pe[7]);
;             p1.x = pk2(pe[8], pe[9]); p1.y = pk2(pe[10], pe[11]); p1.z = pk2(pe[12], pe[13]); p1.w = pk2(pe[14], pe[15]);
;             const bf16x8 pb0 = __builtin_bit_cast(bf16x8, p0), pb1 = __builtin_bit_cast(bf16x8, p1);
; #pragma unroll
;             for (int dt = 0; dt < 4; ++dt) {
;                 const LAS unsigned char* vp = buf + AK_BYTES + (32 * dt + r) * AV_PITCH + (32 * sub + 4 * h) * 2;
;                 const s16x4 lo0 = *(const LAS s16x4*)(vp), hi0 = *(const LAS s16x4*)(vp + 16);
;                 const s16x4 lo1 = *(const LAS s16x4*)(vp + 32), hi1 = *(const LAS s16x4*)(vp + 48);
;                 const bf16x8 va0 = __builtin_shufflevector(lo0, hi0, 0, 1, 2, 3, 4, 5, 6, 7);
;                 const bf16x8 va1 = __builtin_shufflevector(lo1, hi1, 0, 1, 2, 3, 4, 5, 6, 7);
;                 o[dt] = __builtin_amdgcn_mfma_f32_32x32x16_bf16(va0, pb0, o[dt], 0, 0, 0);
;                 o[dt] = __builtin_amdgcn_mfma_f32_32x32x16_bf16(va1, pb1, o[dt], 0, 0, 0);
;             }
;         }
	v_mfma_f32_32x32x16_bf16 v[48:63], v[220:223], v[182:185], v[48:63]
	v_fma_f32 v64, v64, s95, -v178
	v_exp_f32_e32 v64, v64
	v_bfe_i32 v206, v205, 0, 1
	v_fma_f32 v65, v65, s95, -v178
	v_exp_f32_e32 v65, v65
	v_bfe_i32 v207, v205, 1, 1
	v_and_b32_e32 v64, v64, v206
	v_mfma_f32_32x32x16_bf16 v[48:63], v[224:227], v[200:203], v[48:63]
	v_fma_f32 v66, v66, s95, -v178
	v_exp_f32_e32 v66, v66
	v_bfe_i32 v208, v205, 2, 1
	v_and_b32_e32 v65, v65, v207
	v_fma_f32 v67, v67, s95, -v178
	v_exp_f32_e32 v67, v67
	v_bfe_i32 v209, v205, 3, 1
	v_mfma_f32_32x32x16_bf16 v[32:47], v[228:231], v[182:185], v[32:47]
	v_and_b32_e32 v66, v66, v208
	v_fma_f32 v68, v68, s95, -v178
	v_exp_f32_e32 v68, v68
	v_bfe_i32 v210, v205, 8, 1
	v_and_b32_e32 v67, v67, v209
	v_fma_f32 v69, v69, s95, -v178
	v_exp_f32_e32 v69, v69
	v_mfma_f32_32x32x16_bf16 v[32:47], v[232:235], v[200:203], v[32:47]
	v_bfe_i32 v211, v205, 9, 1
	v_and_b32_e32 v68, v68, v210
	v_fma_f32 v70, v70, s95, -v178
	v_exp_f32_e32 v70, v70
	v_bfe_i32 v206, v205, 10, 1
	v_and_b32_e32 v69, v69, v211
	v_fma_f32 v71, v71, s95, -v178
	v_mfma_f32_32x32x16_bf16 v[16:31], v[236:239], v[182:185], v[16:31]
	v_exp_f32_e32 v71, v71
	v_bfe_i32 v207, v205, 11, 1
	v_and_b32_e32 v70, v70, v206
	v_fma_f32 v72, v72, s95, -v178
	v_exp_f32_e32 v72, v72
	v_bfe_i32 v208, v205, 16, 1
	v_and_b32_e32 v71, v71, v207
	v_mfma_f32_32x32x16_bf16 v[16:31], v[240:243], v[200:203], v[16:31]
	v_fma_f32 v73, v73, s95, -v178
	v_exp_f32_e32 v73, v73
	v_bfe_i32 v209, v205, 17, 1
	v_and_b32_e32 v72, v72, v208
	v_fma_f32 v74, v74, s95, -v178
	v_exp_f32_e32 v74, v74
	v_bfe_i32 v210, v205, 18, 1
	v_mfma_f32_32x32x16_bf16 v[0:15], v[244:247], v[182:185], v[0:15]
	v_and_b32_e32 v73, v73, v209
	v_fma_f32 v75, v75, s95, -v178
	v_exp_f32_e32 v75, v75
	v_bfe_i32 v211, v205, 19, 1
	v_and_b32_e32 v74, v74, v210
	v_fma_f32 v76, v76, s95, -v178
	v_exp_f32_e32 v76, v76
	v_mfma_f32_32x32x16_bf16 v[0:15], v[248:251], v[200:203], v[0:15]
	ds_read2_b64 v[220:223], v167 offset0:136 offset1:138
	ds_read2_b64 v[224:227], v167 offset0:140 offset1:142
	ds_read2_b64 v[228:231], v168 offset0:168 offset1:170
	ds_read2_b64 v[232:235], v168 offset0:172 offset1:174
	ds_read2_b64 v[236:239], v169 offset0:200 offset1:202
	ds_read2_b64 v[240:243], v169 offset0:204 offset1:206
	ds_read2_b64 v[244:247], v199 offset0:232 offset1:234
	ds_read2_b64 v[248:251], v199 offset0:236 offset1:238
	v_bfe_i32 v206, v205, 24, 1
	v_and_b32_e32 v75, v75, v211
	v_fma_f32 v77, v77, s95, -v178
	v_exp_f32_e32 v77, v77
	v_bfe_i32 v207, v205, 25, 1
	v_and_b32_e32 v76, v76, v206
	v_fma_f32 v78, v78, s95, -v178
	v_exp_f32_e32 v78, v78
	v_bfe_i32 v208, v205, 26, 1
	v_and_b32_e32 v77, v77, v207
	v_fma_f32 v79, v79, s95, -v178
	v_exp_f32_e32 v79, v79
	v_bfe_i32 v209, v205, 27, 1
	v_and_b32_e32 v78, v78, v208
	v_nop
	v_and_b32_e32 v79, v79, v209
	v_cvt_pk_bf16_f32 v212, v64, v65
	v_cvt_pk_bf16_f32 v213, v66, v67
	v_cvt_pk_bf16_f32 v214, v68, v69
	v_cvt_pk_bf16_f32 v215, v70, v71
	v_cvt_pk_bf16_f32 v216, v72, v73
	v_cvt_pk_bf16_f32 v217, v74, v75
	v_cvt_pk_bf16_f32 v218, v76, v77
	v_cvt_pk_bf16_f32 v219, v78, v79
	v_pk_add_f32 v[64:65], v[64:65], v[66:67]
	v_pk_add_f32 v[68:69], v[68:69], v[70:71]
	v_pk_add_f32 v[72:73], v[72:73], v[74:75]
	v_pk_add_f32 v[76:77], v[76:77], v[78:79]
	v_pk_add_f32 v[64:65], v[64:65], v[68:69]
	v_pk_add_f32 v[72:73], v[72:73], v[76:77]
	v_pk_add_f32 v[64:65], v[64:65], v[72:73]
	v_add_f32_e32 v64, v64, v65
	v_add_f32_e32 v149, v149, v64
	s_waitcnt lgkmcnt(0)
	v_mfma_f32_32x32x16_bf16 v[48:63], v[220:223], v[212:215], v[48:63]
	v_mfma_f32_32x32x16_bf16 v[48:63], v[224:227], v[216:219], v[48:63]
	v_mfma_f32_32x32x16_bf16 v[32:47], v[228:231], v[212:215], v[32:47]
	v_mfma_f32_32x32x16_bf16 v[32:47], v[232:235], v[216:219], v[32:47]
	v_mfma_f32_32x32x16_bf16 v[16:31], v[236:239], v[212:215], v[16:31]
	v_mfma_f32_32x32x16_bf16 v[16:31], v[240:243], v[216:219], v[16:31]
	v_mfma_f32_32x32x16_bf16 v[0:15], v[244:247], v[212:215], v[0:15]
	v_mfma_f32_32x32x16_bf16 v[0:15], v[248:251], v[216:219], v[0:15]
	s_branch .Lat_bottom
.Lat_grpb:
	s_cmp_eq_u32 s18, 0
	s_cbranch_scc1 .Lat_grpb_qk
	v_add3_u32 v166, s24, v151, v180
	v_lshrrev_b32_e32 v204, v147, v176
	v_lshrrev_b32_e32 v205, v147, v177
	v_add_u32_e32 v167, 0x4000, v166
	v_add_u32_e32 v168, 0x5000, v166
	v_add_u32_e32 v169, 0x6000, v166
	v_add_u32_e32 v199, 0x7000, v166
	ds_read2_b64 v[220:223], v167 offset0:128 offset1:130
	ds_read2_b64 v[224:227], v167 offset0:132 offset1:134
	ds_read2_b64 v[228:231], v168 offset0:160 offset1:162
	ds_read2_b64 v[232:235], v168 offset0:164 offset1:166
	ds_read2_b64 v[236:239], v169 offset0:192 offset1:194
	ds_read2_b64 v[240:243], v169 offset0:196 offset1:198
	ds_read2_b64 v[244:247], v199 offset0:224 offset1:226
	ds_read2_b64 v[248:251], v199 offset0:228 offset1:230
	v_fma_f32 v80, v80, s95, -v178
	v_exp_f32_e32 v80, v80
	v_bfe_i32 v206, v204, 0, 1
	v_fma_f32 v81, v81, s95, -v178
	v_exp_f32_e32 v81, v81
	v_bfe_i32 v207, v204, 1, 1
	v_and_b32_e32 v80, v80, v206
	v_fma_f32 v82, v82, s95, -v178
	v_exp_f32_e32 v82, v82
	v_bfe_i32 v208, v204, 2, 1
	v_and_b32_e32 v81, v81, v207
	v_fma_f32 v83, v83, s95, -v178
	v_exp_f32_e32 v83, v83
	v_bfe_i32 v209, v204, 3, 1
	v_and_b32_e32 v82, v82, v208
	v_fma_f32 v84, v84, s95, -v178
	v_exp_f32_e32 v84, v84
	v_bfe_i32 v210, v204, 8, 1
	v_and_b32_e32 v83, v83, v209
	v_fma_f32 v85, v85, s95, -v178
	v_exp_f32_e32 v85, v85
	v_bfe_i32 v211, v204, 9, 1
	v_and_b32_e32 v84, v84, v210
	v_fma_f32 v86, v86, s95, -v178
	v_exp_f32_e32 v86, v86
	v_bfe_i32 v206, v204, 10, 1
	v_and_b32_e32 v85, v85, v211
	v_fma_f32 v87, v87, s95, -v178
	v_exp_f32_e32 v87, v87
	v_bfe_i32 v207, v204, 11, 1
; #define LAS __attribute__((address_space(3)))
; DI unsigned pk2(float lo, float hi) { f32x2 v = {lo, hi}; bf16x2_t b = __builtin_convertvector(v, bf16x2_t); return __builtin_bit_cast(unsigned, b); }
; template <bool MASK>
; DI void attn_unit(LAS unsigned char* lds, const bf16_t* qrow, const bf16_t* kbase, int kpitch, const bf16_t* vtbase, int vtpitch, int ntiles,
;                   const unsigned long long* maskp, bf16_t* orow, float c1, float c2) {
;     ...
;         for (int sub = 0; sub < 2; ++sub) {
;             const unsigned mws = ((unsigned)(mw >> (32 * sub))) >> (4 * h);
;             float pe[16];
; #pragma unroll
;             for (int i = 0; i < 16; ++i) {
;                 float p = __builtin_amdgcn_exp2f(xs[sub][i] * c1 - c2);
;                 if (MASK) { const int m = __builtin_amdgcn_sbfe((int)mws, (i & 3) + 8 * (i >> 2), 1); p = __uint_as_float(__float_as_uint(p) & (unsigned)m); }
;                 l += p; pe[i] = p;
;             }
;             u32x4 p0, p1;
;             p0.x = pk2(pe[0], pe[1]); p0.y = pk2(pe[2], pe[3]); p0.z = pk2(pe[4], pe[5]); p0.w = pk2(pe[6], pe[7]);
;             p1.x = pk2(pe[8], pe[9]); p1.y = pk2(pe[10], pe[11]); p1.z = pk2(pe[12], pe[13]); p1.w = pk2(pe[14], pe[15]);
;             const bf16x8 pb0 = __builtin_bit_cast(bf16x8, p0), pb1 = __builtin_bit_cast(bf16x8, p1);
; #pragma unroll
;             for (int dt = 0; dt < 4; ++dt) {
;                 const LAS unsigned char* vp = buf + AK_BYTES + (32 * dt + r) * AV_PITCH + (32 * sub + 4 * h) * 2;
;                 const s16x4 lo0 = *(const LAS s16x4*)(vp), hi0 = *(const LAS s16x4*)(vp + 16);
;                 const s16x4 lo1 = *(const LAS s16x4*)(vp + 32), hi1 = *(const LAS s16x4*)(vp + 48);
;                 const bf16x8 va0 = __builtin_shufflevector(lo0, hi0, 0, 1, 2, 3, 4, 5, 6, 7);
;                 const bf16x8 va1 = __builtin_shufflevector(lo1, hi1, 0, 1, 2, 3, 4, 5, 6, 7);
;                 o[dt] = __builtin_amdgcn_mfma_f32_32x32x16_bf16(va0, pb0, o[dt], 0, 0, 0);
;                 o[dt] = __builtin_amdgcn_mfma_f32_32x32x16_bf16(va1, pb1, o[dt], 0, 0, 0);
;             }
;         }
	v_and_b32_e32 v86, v86, v206
	v_fma_f32 v88, v88, s95, -v178
	v_exp_f32_e32 v88, v88
	v_bfe_i32 v208, v204, 16, 1
	v_and_b32_e32 v87, v87, v207
	v_fma_f32 v89, v89, s95, -v178
	v_exp_f32_e32 v89, v89
	v_bfe_i32 v209, v204, 17, 1
	v_and_b32_e32 v88, v88, v208
	v_fma_f32 v90, v90, s95, -v178
	v_exp_f32_e32 v90, v90
	v_bfe_i32 v210, v204, 18, 1
	v_and_b32_e32 v89, v89, v209
	v_fma_f32 v91, v91, s95, -v178
	v_exp_f32_e32 v91, v91
	v_bfe_i32 v211, v204, 19, 1
	v_and_b32_e32 v90, v90, v210
	v_fma_f32 v92, v92, s95, -v178
	v_exp_f32_e32 v92, v92
	v_bfe_i32 v206, v204, 24, 1
	v_and_b32_e32 v91, v91, v211
	v_fma_f32 v93, v93, s95, -v178
	v_exp_f32_e32 v93, v93
	v_bfe_i32 v207, v204, 25, 1
	v_and_b32_e32 v92, v92, v206
	v_fma_f32 v94, v94, s95, -v178
	v_exp_f32_e32 v94, v94
	v_bfe_i32 v208, v204, 26, 1
	v_and_b32_e32 v93, v93, v207
	v_fma_f32 v95, v95, s95, -v178
	v_exp_f32_e32 v95, v95
	v_bfe_i32 v209, v204, 27, 1
	v_and_b32_e32 v94, v94, v208
	v_nop
	v_and_b32_e32 v95, v95, v209
	v_cvt_pk_bf16_f32 v182, v80, v81
	v_cvt_pk_bf16_f32 v183, v82, v83
	v_cvt_pk_bf16_f32 v184, v84, v85
	v_cvt_pk_bf16_f32 v185, v86, v87
	v_cvt_pk_bf16_f32 v200, v88, v89
	v_cvt_pk_bf16_f32 v201, v90, v91
	v_cvt_pk_bf16_f32 v202, v92, v93
	v_cvt_pk_bf16_f32 v203, v94, v95
	v_pk_add_f32 v[80:81], v[80:81], v[82:83]
	v_pk_add_f32 v[84:85], v[84:85], v[86:87]
	v_pk_add_f32 v[88:89], v[88:89], v[90:91]
	v_pk_add_f32 v[92:93], v[92:93], v[94:95]
	v_pk_add_f32 v[80:81], v[80:81], v[84:85]
	v_pk_add_f32 v[88:89], v[88:89], v[92:93]
	v_pk_add_f32 v[80:81], v[80:81], v[88:89]
	v_add_f32_e32 v80, v80, v81
	v_add_f32_e32 v149, v149, v80
	s_waitcnt lgkmcnt(0)
	v_mfma_f32_32x32x16_bf16 v[48:63], v[220:223], v[182:185], v[48:63]
	v_fma_f32 v64, v64, s95, -v178
	v_exp_f32_e32 v64, v64
	v_bfe_i32 v206, v205, 0, 1
	v_fma_f32 v65, v65, s95, -v178
	v_exp_f32_e32 v65, v65
	v_bfe_i32 v207, v205, 1, 1
	v_and_b32_e32 v64, v64, v206
	v_mfma_f32_32x32x16_bf16 v[48:63], v[224:227], v[200:203], v[48:63]
	v_fma_f32 v66, v66, s95, -v178
	v_exp_f32_e32 v66, v66
	v_bfe_i32 v208, v205, 2, 1
	v_and_b32_e32 v65, v65, v207
	v_fma_f32 v67, v67, s95, -v178
	v_exp_f32_e32 v67, v67
	v_bfe_i32 v209, v205, 3, 1
	v_mfma_f32_32x32x16_bf16 v[32:47], v[228:231], v[182:185], v[32:47]
	v_and_b32_e32 v66, v66, v208
	v_fma_f32 v68, v68, s95, -v178
	v_exp_f32_e32 v68, v68
	v_bfe_i32 v210, v205, 8, 1
	v_and_b32_e32 v67, v67, v209
	v_fma_f32 v69, v69, s95, -v178
	v_exp_f32_e32 v69, v69
	v_mfma_f32_32x32x16_bf16 v[32:47], v[232:235], v[200:203], v[32:47]
	v_bfe_i32 v211, v205, 9, 1
	v_and_b32_e32 v68, v68, v210
	v_fma_f32 v70, v70, s95, -v178
	v_exp_f32_e32 v70, v70
	v_bfe_i32 v206, v205, 10, 1
	v_and_b32_e32 v69, v69, v211
	v_fma_f32 v71, v71, s95, -v178
	v_mfma_f32_32x32x16_bf16 v[16:31], v[236:239], v[182:185], v[16:31]
	v_exp_f32_e32 v71, v71
	v_bfe_i32 v207, v205, 11, 1
	v_and_b32_e32 v70, v70, v206
	v_fma_f32 v72, v72, s95, -v178
	v_exp_f32_e32 v72, v72
	v_bfe_i32 v208, v205, 16, 1
	v_and_b32_e32 v71, v71, v207
	v_mfma_f32_32x32x16_bf16 v[16:31], v[240:243], v[200:203], v[16:31]
	v_fma_f32 v73, v73, s95, -v178
	v_exp_f32_e32 v73, v73
	v_bfe_i32 v209, v205, 17, 1
	v_and_b32_e32 v72, v72, v208
	v_fma_f32 v74, v74, s95, -v178
	v_exp_f32_e32 v74, v74
	v_bfe_i32 v210, v205, 18, 1
	v_mfma_f32_32x32x16_bf16 v[0:15], v[244:247], v[182:185], v[0:15]
	v_and_b32_e32 v73, v73, v209
	v_fma_f32 v75, v75, s95, -v178
	v_exp_f32_e32 v75, v75
	v_bfe_i32 v211, v205, 19, 1
	v_and_b32_e32 v74, v74, v210
	v_fma_f32 v76, v76, s95, -v178
	v_exp_f32_e32 v76, v76
	v_mfma_f32_32x32x16_bf16 v[0:15], v[248:251], v[200:203], v[0:15]
	ds_read2_b64 v[220:223], v167 offset0:136 offset1:138
	ds_read2_b64 v[224:227], v167 offset0:140 offset1:142
	ds_read2_b64 v[228:231], v168 offset0:168 offset1:170
	ds_read2_b64 v[232:235], v168 offset0:172 offset1:174
	ds_read2_b64 v[236:239], v169 offset0:200 offset1:202
	ds_read2_b64 v[240:243], v169 offset0:204 offset1:206
	ds_read2_b64 v[244:247], v199 offset0:232 offset1:234
	ds_read2_b64 v[248:251], v199 offset0:236 offset1:238
	v_bfe_i32 v206, v205, 24, 1
	v_and_b32_e32 v75, v75, v211
	v_fma_f32 v77, v77, s95, -v178
	v_exp_f32_e32 v77, v77
	v_bfe_i32 v207, v205, 25, 1
	v_and_b32_e32 v76, v76, v206
	v_fma_f32 v78, v78, s95, -v178
	v_exp_f32_e32 v78, v78
	v_bfe_i32 v208, v205, 26, 1
	v_and_b32_e32 v77, v77, v207
	v_fma_f32 v79, v79, s95, -v178
	v_exp_f32_e32 v79, v79
	v_bfe_i32 v209, v205, 27, 1
	v_and_b32_e32 v78, v78, v208
	v_nop
	v_and_b32_e32 v79, v79, v209
	v_cvt_pk_bf16_f32 v212, v64, v65
	v_cvt_pk_bf16_f32 v213, v66, v67
	v_cvt_pk_bf16_f32 v214, v68, v69
	v_cvt_pk_bf16_f32 v215, v70, v71
	v_cvt_pk_bf16_f32 v216, v72, v73
	v_cvt_pk_bf16_f32 v217, v74, v75
	v_cvt_pk_bf16_f32 v218, v76, v77
	v_cvt_pk_bf16_f32 v219, v78, v79
	v_pk_add_f32 v[64:65], v[64:65], v[66:67]
	v_pk_add_f32 v[68:69], v[68:69], v[70:71]
	v_pk_add_f32 v[72:73], v[72:73], v[74:75]
	v_pk_add_f32 v[76:77], v[76:77], v[78:79]
	v_pk_add_f32 v[64:65], v[64:65], v[68:69]
	v_pk_add_f32 v[72:73], v[72:73], v[76:77]
	v_pk_add_f32 v[64:65], v[64:65], v[72:73]
	v_add_f32_e32 v64, v64, v65
	v_add_f32_e32 v149, v149, v64
	s_waitcnt lgkmcnt(0)
	v_mfma_f32_32x32x16_bf16 v[48:63], v[220:223], v[212:215], v[48:63]
	v_mfma_f32_32x32x16_bf16 v[48:63], v[224:227], v[216:219], v[48:63]
	v_mfma_f32_32x32x16_bf16 v[32:47], v[228:231], v[212:215], v[32:47]
	v_mfma_f32_32x32x16_bf16 v[32:47], v[232:235], v[216:219], v[32:47]
	v_mfma_f32_32x32x16_bf16 v[16:31], v[236:239], v[212:215], v[16:31]
	v_mfma_f32_32x32x16_bf16 v[16:31], v[240:243], v[216:219], v[16:31]
	v_mfma_f32_32x32x16_bf16 v[0:15], v[244:247], v[212:215], v[0:15]
	v_mfma_f32_32x32x16_bf16 v[0:15], v[248:251], v[216:219], v[0:15]
; #define LAS __attribute__((address_space(3)))
; template <bool MASK>
; DI void attn_unit(LAS unsigned char* lds, const bf16_t* qrow, const bf16_t* kbase, int kpitch, const bf16_t* vtbase, int vtpitch, int ntiles,
;                   const unsigned long long* maskp, bf16_t* orow, float c1, float c2) {
;     ...
; #pragma unroll
;         for (int sub = 0; sub < 2; ++sub) {
; #pragma unroll
;             for (int i = 0; i < 16; ++i) xs[sub][i] = 0.f;
;             __builtin_amdgcn_s_setprio(1);
; #pragma unroll
;             for (int ks = 0; ks < 8; ++ks) {
;                 const bf16x8 a = *(const LAS bf16x8*)(buf + (32 * sub + r) * AK_PITCH + ks * 32 + h * 16);
;                 xs[sub] = __builtin_amdgcn_mfma_f32_32x32x16_bf16(a, qf[ks], xs[sub], 0, 0, 0);
;             }
;             __builtin_amdgcn_s_setprio(0);
;         }
;     ...
;         if (more) {
;             LAS unsigned char* nb = lds + ((kt + 1) & 1) * ABUF;
;             *(LAS u32x4*)(nb + kl0) = pk[0]; *(LAS u32x4*)(nb + kl1) = pk[1];
;             *(LAS u32x2*)(nb + vl0) = (u32x2){pv[0].x, pv[0].y}; *(LAS u32x2*)(nb + vl0 + 8) = (u32x2){pv[0].z, pv[0].w};
;             *(LAS u32x2*)(nb + vl1) = (u32x2){pv[1].x, pv[1].y}; *(LAS u32x2*)(nb + vl1 + 8) = (u32x2){pv[1].z, pv[1].w};
;         }
;         __syncthreads();
.Lat_grpb_qk:
	s_cmp_lt_i32 s18, s17
	s_cbranch_scc0 .Lat_bottom
	s_setprio 1
	v_add3_u32 v166, s21, v160, v153
	ds_read_b128 v[212:215], v166
	ds_read_b128 v[216:219], v166 offset:32
	ds_read_b128 v[220:223], v166 offset:64
	ds_read_b128 v[224:227], v166 offset:96
	ds_read_b128 v[228:231], v166 offset:128
	ds_read_b128 v[232:235], v166 offset:160
	ds_read_b128 v[236:239], v166 offset:192
	ds_read_b128 v[240:243], v166 offset:224
	ds_read_b128 v[244:247], v166 offset:8704
	ds_read_b128 v[248:251], v166 offset:8736
	ds_read_b128 v[200:203], v166 offset:8768
	ds_read_b128 v[204:207], v166 offset:8800
	ds_read_b128 v[208:211], v166 offset:8832
	ds_read_b128 v[182:185], v166 offset:8864
	s_waitcnt lgkmcnt(13)
	v_mfma_f32_32x32x16_bf16 v[80:95], v[212:215], v[112:115], 0
	s_waitcnt lgkmcnt(12)
	v_mfma_f32_32x32x16_bf16 v[80:95], v[216:219], v[116:119], v[80:95]
	ds_read_b128 v[212:215], v166 offset:8896
	ds_read_b128 v[216:219], v166 offset:8928
	s_waitcnt lgkmcnt(13)
	v_mfma_f32_32x32x16_bf16 v[80:95], v[220:223], v[120:123], v[80:95]
	s_waitcnt lgkmcnt(12)
	v_mfma_f32_32x32x16_bf16 v[80:95], v[224:227], v[124:127], v[80:95]
	s_waitcnt lgkmcnt(11)
	v_mfma_f32_32x32x16_bf16 v[80:95], v[228:231], v[128:131], v[80:95]
	s_waitcnt lgkmcnt(10)
	v_mfma_f32_32x32x16_bf16 v[80:95], v[232:235], v[132:135], v[80:95]
	s_waitcnt lgkmcnt(9)
	v_mfma_f32_32x32x16_bf16 v[80:95], v[236:239], v[136:139], v[80:95]
	s_waitcnt lgkmcnt(8)
	v_mfma_f32_32x32x16_bf16 v[80:95], v[240:243], v[140:143], v[80:95]
	s_waitcnt lgkmcnt(7)
	v_mfma_f32_32x32x16_bf16 v[64:79], v[244:247], v[112:115], 0
	s_waitcnt lgkmcnt(6)
	v_mfma_f32_32x32x16_bf16 v[64:79], v[248:251], v[116:119], v[64:79]
	s_waitcnt lgkmcnt(5)
	v_mfma_f32_32x32x16_bf16 v[64:79], v[200:203], v[120:123], v[64:79]
	s_waitcnt lgkmcnt(4)
	v_mfma_f32_32x32x16_bf16 v[64:79], v[204:207], v[124:127], v[64:79]
	s_waitcnt lgkmcnt(3)
	v_mfma_f32_32x32x16_bf16 v[64:79], v[208:211], v[128:131], v[64:79]
	s_waitcnt lgkmcnt(2)
	v_mfma_f32_32x32x16_bf16 v[64:79], v[182:185], v[132:135], v[64:79]
	s_waitcnt lgkmcnt(1)
	v_mfma_f32_32x32x16_bf16 v[64:79], v[212:215], v[136:139], v[64:79]
	s_waitcnt lgkmcnt(0)
	v_mfma_f32_32x32x16_bf16 v[64:79], v[216:219], v[140:143], v[64:79]
	s_setprio 0
.Lat_bottom:
	s_cmp_lt_i32 s18, s16
	s_cbranch_scc0 .Lat_nowrite
	s_waitcnt vmcnt(1)
	v_add_u32_e32 v166, s23, v146
	ds_write_b128 v166, v[96:99]
	v_add_u32_e32 v166, s23, v148
	ds_write_b128 v166, v[100:103]
	v_add_u32_e32 v166, s23, v150
	v_add_u32_e32 v166, 0x4400, v166
	ds_write2_b64 v166, v[104:105], v[106:107] offset1:1
	v_add_u32_e32 v166, s23, v152
	v_add_u32_e32 v166, 0x4400, v166
	ds_write2_b64 v166, v[108:109], v[110:111] offset1:1
.Lat_nowrite:
	s_waitcnt vmcnt(0)
	v_mov_b64_e32 v[176:177], v[174:175]
	s_mov_b32 s2, s24
	s_mov_b32 s24, s21
	s_mov_b32 s21, s23
	s_mov_b32 s23, s2
	s_add_i32 s18, s18, 1
	s_cmp_le_i32 s18, s17
	s_waitcnt lgkmcnt(0)
	s_barrier
	s_cbranch_scc1 .Lat_top
	v_mov_b32_e32 v64, v147
	s_branch .LBB0_1238
